# grid barrier: L1 invalidate issued before the wait instead of after it (overlaps with write-back / spin), 10 barrier instances
# speedup vs baseline: 1.0259x; 1.0003x over previous
.LBB0_108:
	s_lshl_b32 s14, s14, 6
	s_add_i32 s6, s14, 0x500
	s_mov_b32 s7, 0
	s_lshl_b64 s[4:5], s[6:7], 2
	s_add_u32 s4, s46, s4
	s_addc_u32 s5, s47, s5
	v_mov_b32_e32 v1, 1
	v_mov_b64_e32 v[4:5], s[4:5]
	flat_atomic_add v1, v[4:5], v1 sc0
	v_cvt_f32_u32_e32 v3, v2
	v_sub_u32_e32 v4, 0, v2
	v_rcp_iflag_f32_e32 v3, v3
	s_nop 0
	v_mul_f32_e32 v3, 0x4f7ffffe, v3
	v_cvt_u32_f32_e32 v3, v3
	v_mul_lo_u32 v4, v4, v3
	v_mul_hi_u32 v4, v3, v4
	v_add_u32_e32 v3, v3, v4
	s_waitcnt vmcnt(0) lgkmcnt(0)
	v_mul_hi_u32 v3, v1, v3
	v_mul_lo_u32 v5, v3, v2
	v_add_u32_e32 v4, 1, v1
	v_sub_u32_e32 v1, v1, v5
	v_add_u32_e32 v6, 1, v3
	v_cmp_ge_u32_e32 vcc, v1, v2
	v_sub_u32_e32 v5, v1, v2
	s_nop 0
	v_cndmask_b32_e32 v3, v3, v6, vcc
	v_cndmask_b32_e32 v1, v1, v5, vcc
	v_add_u32_e32 v5, 1, v3
	v_cmp_ge_u32_e32 vcc, v1, v2
	s_nop 1
	v_cndmask_b32_e32 v1, v3, v5, vcc
	v_mad_u64_u32 v[2:3], s[4:5], v2, v1, v[2:3]
	v_cmp_ne_u32_e32 vcc, v4, v2
	s_and_saveexec_b64 s[4:5], vcc
	s_xor_b64 s[4:5], exec, s[4:5]
	s_cbranch_execz .LBB0_121
	s_add_i32 s6, s14, 0x900
	s_lshl_b64 s[6:7], s[6:7], 2
	s_add_u32 s8, s46, s6
	s_addc_u32 s9, s47, s7
	v_mov_b64_e32 v[2:3], s[8:9]
	buffer_inv sc1
	flat_load_dword v0, v[2:3] sc1
	s_waitcnt vmcnt(0) lgkmcnt(0)
	v_cmp_eq_u32_e32 vcc, v0, v1
	s_and_saveexec_b64 s[6:7], vcc
	s_cbranch_execz .LBB0_120
	s_mov_b32 s15, 1
	s_mov_b64 s[10:11], 0
	s_branch .LBB0_112

.LBB0_120:
	s_or_b64 exec, exec, s[6:7]
	s_waitcnt vmcnt(0) lgkmcnt(0)
	s_waitcnt vmcnt(0)
.LBB0_121:
	s_andn2_saveexec_b64 s[4:5], s[4:5]
	s_cbranch_execz .LBB0_137
	v_mov_b32_e32 v1, s46
	v_add_co_u32_e32 v2, vcc, 0x3000, v1
	v_mov_b32_e32 v1, s47
	buffer_wbl2 sc1
	buffer_inv sc1
	s_waitcnt vmcnt(0)
	v_addc_co_u32_e32 v3, vcc, 0, v1, vcc
	v_mov_b32_e32 v1, 1
	flat_atomic_add v1, v[2:3], v1 offset:1024 sc0
	v_cvt_f32_u32_e32 v2, v0
	v_sub_u32_e32 v3, 0, v0
	s_add_u32 s4, s46, 0x3500
	s_addc_u32 s5, s47, 0
	v_rcp_iflag_f32_e32 v2, v2
	s_mov_b64 s[8:9], -1
	v_mul_f32_e32 v2, 0x4f7ffffe, v2
	v_cvt_u32_f32_e32 v2, v2
	v_mul_lo_u32 v3, v3, v2
	v_mul_hi_u32 v3, v2, v3
	v_add_u32_e32 v2, v2, v3
	s_waitcnt vmcnt(0) lgkmcnt(0)
	v_mul_hi_u32 v2, v1, v2
	v_mul_lo_u32 v4, v2, v0
	v_add_u32_e32 v3, 1, v1
	v_sub_u32_e32 v1, v1, v4
	v_add_u32_e32 v5, 1, v2
	v_cmp_ge_u32_e32 vcc, v1, v0
	v_sub_u32_e32 v4, v1, v0
	s_nop 0
	v_cndmask_b32_e32 v2, v2, v5, vcc
	v_cndmask_b32_e32 v1, v1, v4, vcc
	v_add_u32_e32 v4, 1, v2
	v_cmp_ge_u32_e32 vcc, v1, v0
	s_nop 1
	v_cndmask_b32_e32 v2, v2, v4, vcc
	v_mad_u64_u32 v[0:1], s[6:7], v0, v2, v[0:1]
	v_cmp_ne_u32_e32 vcc, v3, v0
	v_mov_b64_e32 v[0:1], s[4:5]
	s_and_saveexec_b64 s[6:7], vcc
	s_cbranch_execz .LBB0_134
	v_mov_b64_e32 v[0:1], s[4:5]
	flat_load_dword v0, v[0:1] sc1
	s_mov_b64 s[12:13], 0
	s_waitcnt vmcnt(0) lgkmcnt(0)
	v_cmp_eq_u32_e32 vcc, v0, v2
	s_and_saveexec_b64 s[10:11], vcc
	s_cbranch_execz .LBB0_133
	s_add_u32 s8, s46, 0x200
	s_addc_u32 s9, s47, 0
	s_mov_b32 s15, 1
	s_branch .LBB0_126

.LBB0_136:
	s_or_b64 exec, exec, s[4:5]
	s_add_i32 s4, s14, 0x900
	s_mov_b32 s5, 0
	s_lshl_b64 s[4:5], s[4:5], 2
	s_add_u32 s4, s46, s4
	s_addc_u32 s5, s47, s5
	v_mov_b32_e32 v2, 1
	v_mov_b64_e32 v[0:1], s[4:5]
	s_waitcnt vmcnt(0) lgkmcnt(0)
	flat_atomic_add v[0:1], v2
	s_waitcnt vmcnt(0)

.LBB0_138:
	s_or_b64 exec, exec, s[4:5]
	s_add_i32 s52, s0, 0x900
	s_lshl_b64 s[0:1], s[52:53], 2
	s_add_u32 s0, s46, s0
	s_addc_u32 s1, s47, s1
	v_mov_b64_e32 v[0:1], s[0:1]
	s_waitcnt vmcnt(0) lgkmcnt(0)
	flat_atomic_add v[0:1], v222
	s_waitcnt vmcnt(0)

.LBB0_476:
	s_lshl_b32 s0, s0, 6
	s_add_i32 s52, s0, 0x500
	s_lshl_b64 s[4:5], s[52:53], 2
	s_add_u32 s4, s46, s4
	s_addc_u32 s5, s47, s5
	v_mov_b64_e32 v[6:7], s[4:5]
	flat_atomic_add v3, v[6:7], v222 sc0
	v_cvt_f32_u32_e32 v1, v4
	v_sub_u32_e32 v5, 0, v4
	v_rcp_iflag_f32_e32 v1, v1
	s_nop 0
	v_mul_f32_e32 v1, 0x4f7ffffe, v1
	v_cvt_u32_f32_e32 v1, v1
	v_mul_lo_u32 v5, v5, v1
	v_mul_hi_u32 v5, v1, v5
	v_add_u32_e32 v1, v1, v5
	s_waitcnt vmcnt(0) lgkmcnt(0)
	v_mul_hi_u32 v1, v3, v1
	v_mul_lo_u32 v5, v1, v4
	v_sub_u32_e32 v5, v3, v5
	v_cmp_ge_u32_e32 vcc, v5, v4
	v_add_u32_e32 v6, 1, v1
	v_add_u32_e32 v3, 1, v3
	v_cndmask_b32_e32 v1, v1, v6, vcc
	v_sub_u32_e32 v6, v5, v4
	v_cndmask_b32_e32 v5, v5, v6, vcc
	v_cmp_ge_u32_e32 vcc, v5, v4
	v_add_u32_e32 v5, 1, v1
	s_nop 0
	v_cndmask_b32_e32 v1, v1, v5, vcc
	v_mad_u64_u32 v[4:5], s[4:5], v4, v1, v[4:5]
	v_cmp_ne_u32_e32 vcc, v3, v4
	s_and_saveexec_b64 s[4:5], vcc
	s_xor_b64 s[4:5], exec, s[4:5]
	s_cbranch_execz .LBB0_489
	s_add_i32 s52, s0, 0x900
	s_lshl_b64 s[6:7], s[52:53], 2
	s_add_u32 s8, s46, s6
	s_addc_u32 s9, s47, s7
	v_mov_b64_e32 v[4:5], s[8:9]
	buffer_inv sc1
	flat_load_dword v0, v[4:5] sc1
	s_waitcnt vmcnt(0) lgkmcnt(0)
	v_cmp_eq_u32_e32 vcc, v0, v1
	s_and_saveexec_b64 s[6:7], vcc
	s_cbranch_execz .LBB0_488
	s_mov_b32 s1, 1
	s_mov_b64 s[10:11], 0
	s_branch .LBB0_480

.LBB0_489:
	s_andn2_saveexec_b64 s[4:5], s[4:5]
	s_cbranch_execz .LBB0_505
	v_mov_b32_e32 v1, s46
	v_add_co_u32_e32 v4, vcc, 0x3000, v1
	v_mov_b32_e32 v1, s47
	buffer_wbl2 sc1
	buffer_inv sc1
	s_waitcnt vmcnt(0)
	v_addc_co_u32_e32 v5, vcc, 0, v1, vcc
	flat_atomic_add v1, v[4:5], v222 offset:1024 sc0
	v_cvt_f32_u32_e32 v3, v0
	v_sub_u32_e32 v4, 0, v0
	s_mov_b64 s[8:9], -1
	v_rcp_iflag_f32_e32 v3, v3
	s_nop 0
	v_mul_f32_e32 v3, 0x4f7ffffe, v3
	v_cvt_u32_f32_e32 v3, v3
	v_mul_lo_u32 v4, v4, v3
	v_mul_hi_u32 v4, v3, v4
	v_add_u32_e32 v3, v3, v4
	s_waitcnt vmcnt(0) lgkmcnt(0)
	v_mul_hi_u32 v3, v1, v3
	v_mul_lo_u32 v4, v3, v0
	v_sub_u32_e32 v4, v1, v4
	v_cmp_ge_u32_e32 vcc, v4, v0
	v_add_u32_e32 v5, 1, v3
	s_nop 0
	v_cndmask_b32_e32 v3, v3, v5, vcc
	v_sub_u32_e32 v5, v4, v0
	v_cndmask_b32_e32 v4, v4, v5, vcc
	v_cmp_ge_u32_e32 vcc, v4, v0
	v_add_u32_e32 v4, 1, v3
	s_nop 0
	v_cndmask_b32_e32 v3, v3, v4, vcc
	v_add_u32_e32 v4, 1, v1
	v_mad_u64_u32 v[0:1], s[4:5], v0, v3, v[0:1]
	s_add_u32 s4, s46, 0x3500
	s_addc_u32 s5, s47, 0
	v_cmp_ne_u32_e32 vcc, v4, v0
	v_mov_b64_e32 v[0:1], s[4:5]
	s_and_saveexec_b64 s[6:7], vcc
	s_cbranch_execz .LBB0_502
	v_mov_b64_e32 v[0:1], s[4:5]
	flat_load_dword v0, v[0:1] sc1
	s_mov_b64 s[12:13], 0
	s_waitcnt vmcnt(0) lgkmcnt(0)
	v_cmp_eq_u32_e32 vcc, v0, v3
	s_and_saveexec_b64 s[10:11], vcc
	s_cbranch_execz .LBB0_501
	s_add_u32 s8, s46, 0x200
	s_addc_u32 s9, s47, 0
	s_mov_b32 s1, 1
	s_branch .LBB0_494

.LBB0_523:
	s_lshl_b32 s0, s0, 6
	s_add_i32 s52, s0, 0x500
	s_lshl_b64 s[4:5], s[52:53], 2
	s_add_u32 s4, s74, s4
	s_addc_u32 s5, s75, s5
	v_mov_b64_e32 v[6:7], s[4:5]
	flat_atomic_add v3, v[6:7], v222 sc0
	v_cvt_f32_u32_e32 v1, v4
	v_sub_u32_e32 v5, 0, v4
	v_rcp_iflag_f32_e32 v1, v1
	s_nop 0
	v_mul_f32_e32 v1, 0x4f7ffffe, v1
	v_cvt_u32_f32_e32 v1, v1
	v_mul_lo_u32 v5, v5, v1
	v_mul_hi_u32 v5, v1, v5
	v_add_u32_e32 v1, v1, v5
	s_waitcnt vmcnt(0) lgkmcnt(0)
	v_mul_hi_u32 v1, v3, v1
	v_mul_lo_u32 v5, v1, v4
	v_sub_u32_e32 v5, v3, v5
	v_cmp_ge_u32_e32 vcc, v5, v4
	v_add_u32_e32 v6, 1, v1
	v_add_u32_e32 v3, 1, v3
	v_cndmask_b32_e32 v1, v1, v6, vcc
	v_sub_u32_e32 v6, v5, v4
	v_cndmask_b32_e32 v5, v5, v6, vcc
	v_cmp_ge_u32_e32 vcc, v5, v4
	v_add_u32_e32 v5, 1, v1
	s_nop 0
	v_cndmask_b32_e32 v1, v1, v5, vcc
	v_mad_u64_u32 v[4:5], s[4:5], v4, v1, v[4:5]
	v_cmp_ne_u32_e32 vcc, v3, v4
	s_and_saveexec_b64 s[4:5], vcc
	s_xor_b64 s[4:5], exec, s[4:5]
	s_cbranch_execz .LBB0_536
	s_add_i32 s52, s0, 0x900
	s_lshl_b64 s[6:7], s[52:53], 2
	s_add_u32 s8, s74, s6
	s_addc_u32 s9, s75, s7
	v_mov_b64_e32 v[4:5], s[8:9]
	buffer_inv sc1
	flat_load_dword v0, v[4:5] sc1
	s_waitcnt vmcnt(0) lgkmcnt(0)
	v_cmp_eq_u32_e32 vcc, v0, v1
	s_and_saveexec_b64 s[6:7], vcc
	s_cbranch_execz .LBB0_535
	s_mov_b32 s1, 1
	s_mov_b64 s[10:11], 0
	s_branch .LBB0_527

.LBB0_536:
	s_andn2_saveexec_b64 s[4:5], s[4:5]
	s_cbranch_execz .LBB0_552
	v_mov_b32_e32 v1, s74
	v_add_co_u32_e32 v4, vcc, 0x3000, v1
	v_mov_b32_e32 v1, s75
	buffer_wbl2 sc1
	buffer_inv sc1
	s_waitcnt vmcnt(0)
	v_addc_co_u32_e32 v5, vcc, 0, v1, vcc
	flat_atomic_add v1, v[4:5], v222 offset:1024 sc0
	v_cvt_f32_u32_e32 v3, v0
	v_sub_u32_e32 v4, 0, v0
	s_mov_b64 s[8:9], -1
	v_rcp_iflag_f32_e32 v3, v3
	s_nop 0
	v_mul_f32_e32 v3, 0x4f7ffffe, v3
	v_cvt_u32_f32_e32 v3, v3
	v_mul_lo_u32 v4, v4, v3
	v_mul_hi_u32 v4, v3, v4
	v_add_u32_e32 v3, v3, v4
	s_waitcnt vmcnt(0) lgkmcnt(0)
	v_mul_hi_u32 v3, v1, v3
	v_mul_lo_u32 v4, v3, v0
	v_sub_u32_e32 v4, v1, v4
	v_cmp_ge_u32_e32 vcc, v4, v0
	v_add_u32_e32 v5, 1, v3
	s_nop 0
	v_cndmask_b32_e32 v3, v3, v5, vcc
	v_sub_u32_e32 v5, v4, v0
	v_cndmask_b32_e32 v4, v4, v5, vcc
	v_cmp_ge_u32_e32 vcc, v4, v0
	v_add_u32_e32 v4, 1, v3
	s_nop 0
	v_cndmask_b32_e32 v3, v3, v4, vcc
	v_add_u32_e32 v4, 1, v1
	v_mad_u64_u32 v[0:1], s[4:5], v0, v3, v[0:1]
	s_add_u32 s4, s74, 0x3500
	s_addc_u32 s5, s75, 0
	v_cmp_ne_u32_e32 vcc, v4, v0
	v_mov_b64_e32 v[0:1], s[4:5]
	s_and_saveexec_b64 s[6:7], vcc
	s_cbranch_execz .LBB0_549
	v_mov_b64_e32 v[0:1], s[4:5]
	flat_load_dword v0, v[0:1] sc1
	s_mov_b64 s[12:13], 0
	s_waitcnt vmcnt(0) lgkmcnt(0)
	v_cmp_eq_u32_e32 vcc, v0, v3
	s_and_saveexec_b64 s[10:11], vcc
	s_cbranch_execz .LBB0_548
	s_add_u32 s8, s74, 0x200
	s_addc_u32 s9, s75, 0
	s_mov_b32 s1, 1
	s_branch .LBB0_541

.LBB0_551:
	s_or_b64 exec, exec, s[4:5]
	s_add_i32 s52, s0, 0x900
	s_lshl_b64 s[0:1], s[52:53], 2
	s_add_u32 s0, s74, s0
	s_addc_u32 s1, s75, s1
	v_mov_b64_e32 v[0:1], s[0:1]
	s_waitcnt vmcnt(0) lgkmcnt(0)
	flat_atomic_add v[0:1], v222
	s_waitcnt vmcnt(0)

.LBB0_940:
	s_andn2_saveexec_b64 s[4:5], s[4:5]
	s_cbranch_execz .LBB0_956
	v_mov_b32_e32 v1, s74
	v_add_co_u32_e32 v4, vcc, 0x3000, v1
	v_mov_b32_e32 v1, s75
	buffer_wbl2 sc1
	buffer_inv sc1
	s_waitcnt vmcnt(0)
	v_addc_co_u32_e32 v5, vcc, 0, v1, vcc
	flat_atomic_add v1, v[4:5], v222 offset:1024 sc0
	v_cvt_f32_u32_e32 v3, v0
	v_sub_u32_e32 v4, 0, v0
	s_mov_b64 s[10:11], -1
	v_rcp_iflag_f32_e32 v3, v3
	s_nop 0
	v_mul_f32_e32 v3, 0x4f7ffffe, v3
	v_cvt_u32_f32_e32 v3, v3
	v_mul_lo_u32 v4, v4, v3
	v_mul_hi_u32 v4, v3, v4
	v_add_u32_e32 v3, v3, v4
	s_waitcnt vmcnt(0) lgkmcnt(0)
	v_mul_hi_u32 v3, v1, v3
	v_mul_lo_u32 v4, v3, v0
	v_sub_u32_e32 v4, v1, v4
	v_cmp_ge_u32_e32 vcc, v4, v0
	v_add_u32_e32 v5, 1, v3
	s_nop 0
	v_cndmask_b32_e32 v3, v3, v5, vcc
	v_sub_u32_e32 v5, v4, v0
	v_cndmask_b32_e32 v4, v4, v5, vcc
	v_cmp_ge_u32_e32 vcc, v4, v0
	v_add_u32_e32 v4, 1, v3
	s_nop 0
	v_cndmask_b32_e32 v3, v3, v4, vcc
	v_add_u32_e32 v4, 1, v1
	v_mad_u64_u32 v[0:1], s[6:7], v0, v3, v[0:1]
	s_add_u32 s6, s74, 0x3500
	s_addc_u32 s7, s75, 0
	v_cmp_ne_u32_e32 vcc, v4, v0
	v_mov_b64_e32 v[0:1], s[6:7]
	s_and_saveexec_b64 s[8:9], vcc
	s_cbranch_execz .LBB0_953
	v_mov_b64_e32 v[0:1], s[6:7]
	flat_load_dword v0, v[0:1] sc1
	s_mov_b64 s[16:17], 0
	s_waitcnt vmcnt(0) lgkmcnt(0)
	v_cmp_eq_u32_e32 vcc, v0, v3
	s_and_saveexec_b64 s[12:13], vcc
	s_cbranch_execz .LBB0_952
	s_add_u32 s10, s74, 0x200
	s_addc_u32 s11, s75, 0
	s_mov_b32 s1, 1
	s_branch .LBB0_945

.LBB0_955:
	s_or_b64 exec, exec, s[6:7]
	s_add_i32 s52, s0, 0x900
	s_lshl_b64 s[0:1], s[52:53], 2
	s_add_u32 s0, s74, s0
	s_addc_u32 s1, s75, s1
	v_mov_b64_e32 v[0:1], s[0:1]
	s_waitcnt vmcnt(0) lgkmcnt(0)
	flat_atomic_add v[0:1], v222
	s_waitcnt vmcnt(0)

.LBB0_1013:
	s_lshl_b32 s0, s0, 6
	s_add_i32 s52, s0, 0x500
	s_lshl_b64 s[6:7], s[52:53], 2
	s_add_u32 s6, s46, s6
	s_addc_u32 s7, s47, s7
	v_mov_b64_e32 v[6:7], s[6:7]
	flat_atomic_add v3, v[6:7], v222 sc0
	v_cvt_f32_u32_e32 v1, v4
	v_sub_u32_e32 v5, 0, v4
	v_rcp_iflag_f32_e32 v1, v1
	s_nop 0
	v_mul_f32_e32 v1, 0x4f7ffffe, v1
	v_cvt_u32_f32_e32 v1, v1
	v_mul_lo_u32 v5, v5, v1
	v_mul_hi_u32 v5, v1, v5
	v_add_u32_e32 v1, v1, v5
	s_waitcnt vmcnt(0) lgkmcnt(0)
	v_mul_hi_u32 v1, v3, v1
	v_mul_lo_u32 v5, v1, v4
	v_sub_u32_e32 v5, v3, v5
	v_cmp_ge_u32_e32 vcc, v5, v4
	v_add_u32_e32 v6, 1, v1
	v_add_u32_e32 v3, 1, v3
	v_cndmask_b32_e32 v1, v1, v6, vcc
	v_sub_u32_e32 v6, v5, v4
	v_cndmask_b32_e32 v5, v5, v6, vcc
	v_cmp_ge_u32_e32 vcc, v5, v4
	v_add_u32_e32 v5, 1, v1
	s_nop 0
	v_cndmask_b32_e32 v1, v1, v5, vcc
	v_mad_u64_u32 v[4:5], s[6:7], v4, v1, v[4:5]
	v_cmp_ne_u32_e32 vcc, v3, v4
	s_and_saveexec_b64 s[6:7], vcc
	s_xor_b64 s[6:7], exec, s[6:7]
	s_cbranch_execz .LBB0_1026
	s_add_i32 s52, s0, 0x900
	s_lshl_b64 s[8:9], s[52:53], 2
	s_add_u32 s10, s46, s8
	s_addc_u32 s11, s47, s9
	v_mov_b64_e32 v[4:5], s[10:11]
	buffer_inv sc1
	flat_load_dword v0, v[4:5] sc1
	s_waitcnt vmcnt(0) lgkmcnt(0)
	v_cmp_eq_u32_e32 vcc, v0, v1
	s_and_saveexec_b64 s[8:9], vcc
	s_cbranch_execz .LBB0_1025
	s_mov_b32 s1, 1
	s_mov_b64 s[12:13], 0
	s_branch .LBB0_1017

.LBB0_1025:
	s_or_b64 exec, exec, s[8:9]
	s_waitcnt vmcnt(0) lgkmcnt(0)
	s_waitcnt vmcnt(0)
.LBB0_1026:
	s_andn2_saveexec_b64 s[6:7], s[6:7]
	s_cbranch_execz .LBB0_1042
	v_mov_b32_e32 v1, s46
	v_add_co_u32_e32 v4, vcc, 0x3000, v1
	v_mov_b32_e32 v1, s47
	buffer_wbl2 sc1
	buffer_inv sc1
	s_waitcnt vmcnt(0)
	v_addc_co_u32_e32 v5, vcc, 0, v1, vcc
	flat_atomic_add v1, v[4:5], v222 offset:1024 sc0
	v_cvt_f32_u32_e32 v3, v0
	v_sub_u32_e32 v4, 0, v0
	s_mov_b64 s[10:11], -1
	v_rcp_iflag_f32_e32 v3, v3
	s_nop 0
	v_mul_f32_e32 v3, 0x4f7ffffe, v3
	v_cvt_u32_f32_e32 v3, v3
	v_mul_lo_u32 v4, v4, v3
	v_mul_hi_u32 v4, v3, v4
	v_add_u32_e32 v3, v3, v4
	s_waitcnt vmcnt(0) lgkmcnt(0)
	v_mul_hi_u32 v3, v1, v3
	v_mul_lo_u32 v4, v3, v0
	v_sub_u32_e32 v4, v1, v4
	v_cmp_ge_u32_e32 vcc, v4, v0
	v_add_u32_e32 v5, 1, v3
	s_nop 0
	v_cndmask_b32_e32 v3, v3, v5, vcc
	v_sub_u32_e32 v5, v4, v0
	v_cndmask_b32_e32 v4, v4, v5, vcc
	v_cmp_ge_u32_e32 vcc, v4, v0
	v_add_u32_e32 v4, 1, v3
	s_nop 0
	v_cndmask_b32_e32 v3, v3, v4, vcc
	v_add_u32_e32 v4, 1, v1
	v_mad_u64_u32 v[0:1], s[6:7], v0, v3, v[0:1]
	s_add_u32 s6, s46, 0x3500
	s_addc_u32 s7, s47, 0
	v_cmp_ne_u32_e32 vcc, v4, v0
	v_mov_b64_e32 v[0:1], s[6:7]
	s_and_saveexec_b64 s[8:9], vcc
	s_cbranch_execz .LBB0_1039
	v_mov_b64_e32 v[0:1], s[6:7]
	flat_load_dword v0, v[0:1] sc1
	s_mov_b64 s[16:17], 0
	s_waitcnt vmcnt(0) lgkmcnt(0)
	v_cmp_eq_u32_e32 vcc, v0, v3
	s_and_saveexec_b64 s[12:13], vcc
	s_cbranch_execz .LBB0_1038
	s_add_u32 s10, s46, 0x200
	s_addc_u32 s11, s47, 0
	s_mov_b32 s1, 1
	s_branch .LBB0_1031

.LBB0_1041:
	s_or_b64 exec, exec, s[6:7]
	s_add_i32 s52, s0, 0x900
	s_lshl_b64 s[0:1], s[52:53], 2
	s_add_u32 s0, s46, s0
	s_addc_u32 s1, s47, s1
	v_mov_b64_e32 v[0:1], s[0:1]
	s_waitcnt vmcnt(0) lgkmcnt(0)
	flat_atomic_add v[0:1], v222
	s_waitcnt vmcnt(0)

.LBB0_1257:
	v_mov_b32_e32 v1, s46
	v_add_co_u32_e32 v4, vcc, 0x3000, v1
	v_mov_b32_e32 v1, s47
	buffer_wbl2 sc1
	buffer_inv sc1
	s_waitcnt vmcnt(0)
	v_addc_co_u32_e32 v5, vcc, 0, v1, vcc
	flat_atomic_add v1, v[4:5], v222 offset:1024 sc0
	v_cvt_f32_u32_e32 v3, v0
	v_sub_u32_e32 v4, 0, v0
	s_mov_b64 s[8:9], -1
	v_rcp_iflag_f32_e32 v3, v3
	s_nop 0
	v_mul_f32_e32 v3, 0x4f7ffffe, v3
	v_cvt_u32_f32_e32 v3, v3
	v_mul_lo_u32 v4, v4, v3
	v_mul_hi_u32 v4, v3, v4
	v_add_u32_e32 v3, v3, v4
	s_waitcnt vmcnt(0) lgkmcnt(0)
	v_mul_hi_u32 v3, v1, v3
	v_mul_lo_u32 v4, v3, v0
	v_sub_u32_e32 v4, v1, v4
	v_cmp_ge_u32_e32 vcc, v4, v0
	v_add_u32_e32 v5, 1, v3
	s_nop 0
	v_cndmask_b32_e32 v3, v3, v5, vcc
	v_sub_u32_e32 v5, v4, v0
	v_cndmask_b32_e32 v4, v4, v5, vcc
	v_cmp_ge_u32_e32 vcc, v4, v0
	v_add_u32_e32 v4, 1, v3
	s_nop 0
	v_cndmask_b32_e32 v3, v3, v4, vcc
	v_add_u32_e32 v4, 1, v1
	v_mad_u64_u32 v[0:1], s[4:5], v0, v3, v[0:1]
	s_add_u32 s4, s46, 0x3500
	s_addc_u32 s5, s47, 0
	v_cmp_ne_u32_e32 vcc, v4, v0
	v_mov_b64_e32 v[0:1], s[4:5]
	s_and_saveexec_b64 s[6:7], vcc
	s_cbranch_execz .LBB0_1269
	v_mov_b64_e32 v[0:1], s[4:5]
	flat_load_dword v0, v[0:1] sc1
	s_mov_b64 s[12:13], 0
	s_waitcnt vmcnt(0) lgkmcnt(0)
	v_cmp_eq_u32_e32 vcc, v0, v3
	s_and_saveexec_b64 s[10:11], vcc
	s_cbranch_execz .LBB0_1268
	s_add_u32 s8, s46, 0x200
	s_addc_u32 s9, s47, 0
	s_mov_b32 s1, 1
	s_branch .LBB0_1261
